# v132 + nt on norm-phase bf16 H stores (streaming hint experiment)
# baseline (speedup 1.0000x reference)
.LBB0_475:
	s_or_b64 exec, exec, s[36:37]
	s_waitcnt vmcnt(0)
	v_mul_f32_e32 v0, v63, v63
	v_mul_f32_e32 v67, v51, v51
	v_fmac_f32_e32 v0, v62, v62
	v_fmac_f32_e32 v67, v50, v50
	v_fmac_f32_e32 v0, v64, v64
	v_fmac_f32_e32 v67, v52, v52
	v_fmac_f32_e32 v0, v65, v65
	v_fmac_f32_e32 v67, v53, v53
	v_add_f32_e32 v0, v67, v0
	v_mul_f32_e32 v67, v47, v47
	v_fmac_f32_e32 v67, v46, v46
	v_fmac_f32_e32 v67, v48, v48
	v_fmac_f32_e32 v67, v49, v49
	v_add_f32_e32 v0, v67, v0
	v_mul_f32_e32 v67, v31, v31
	v_fmac_f32_e32 v67, v30, v30
	v_fmac_f32_e32 v67, v32, v32
	v_fmac_f32_e32 v67, v33, v33
	v_add_f32_e32 v0, v67, v0
	v_min_i32_e32 v67, 0x8000, v66
	v_ashrrev_i32_e32 v67, 12, v67
	v_lshl_add_u32 v222, v67, 13, v223
	v_mul_i32_i24_e32 v98, 0x1800, v67
	v_ashrrev_i32_e32 v99, 31, v98
	v_lshl_add_u64 v[100:101], v[98:99], 2, s[22:23]
	s_mov_b64 s[10:11], 0x1000
	v_lshl_add_u64 v[98:99], v[100:101], 0, s[10:11]
	v_mov_b32_e32 v85, v1
	v_lshl_add_u64 v[106:107], v[98:99], 0, v[84:85]
	ds_read_b128 v[102:105], v242
	ds_read_b128 v[114:117], v222 offset:4096
	v_lshl_add_u64 v[100:101], v[100:101], 0, v[84:85]
	ds_read_b128 v[118:121], v222
	v_mov_b32_e32 v87, v1
	v_mov_b32_e32 v89, v1
	v_mov_b32_e32 v91, v1
	ds_read_b128 v[168:171], v242 offset:1024
	v_lshl_add_u64 v[172:173], v[98:99], 0, v[86:87]
	ds_read_b128 v[172:175], v222 offset:5120
	ds_read_b128 v[176:179], v222 offset:1024
	ds_read_b128 v[180:183], v242 offset:2048
	v_lshl_add_u64 v[184:185], v[98:99], 0, v[88:89]
	ds_read_b128 v[184:187], v222 offset:6144
	ds_read_b128 v[188:191], v222 offset:2048
	ds_read_b128 v[192:195], v242 offset:3072
	v_lshl_add_u64 v[196:197], v[98:99], 0, v[90:91]
	ds_read_b128 v[196:199], v222 offset:7168
	ds_read_b128 v[200:203], v222 offset:3072
	ds_bpermute_b32 v67, v108, v0
	v_mov_b32_e32 v87, v1
	v_mov_b32_e32 v89, v1
	v_mov_b32_e32 v91, v1
	s_waitcnt lgkmcnt(0)
	v_add_f32_e32 v0, v0, v67
	ds_bpermute_b32 v67, v109, v0
	s_waitcnt lgkmcnt(0)
	v_add_f32_e32 v0, v0, v67
	ds_bpermute_b32 v67, v110, v0
	s_waitcnt lgkmcnt(0)
	v_add_f32_e32 v0, v0, v67
	ds_bpermute_b32 v67, v111, v0
	s_waitcnt lgkmcnt(0)
	v_add_f32_e32 v0, v0, v67
	ds_bpermute_b32 v67, v112, v0
	s_waitcnt lgkmcnt(0)
	v_add_f32_e32 v0, v0, v67
	ds_bpermute_b32 v67, v113, v0
	s_waitcnt lgkmcnt(0)
	v_add_f32_e32 v0, v0, v67
	v_fmamk_f32 v0, v0, 0x3a800000, v218
	v_cmp_gt_f32_e32 vcc, s13, v0
	v_mul_f32_e32 v67, 0x4b800000, v0
	s_nop 0
	v_cndmask_b32_e32 v0, v0, v67, vcc
	v_rsq_f32_e32 v0, v0
	s_nop 0
	v_mul_f32_e32 v67, 0x45800000, v0
	v_cndmask_b32_e32 v0, v0, v67, vcc
	v_pk_mul_f32 v[64:65], v[64:65], v[0:1] op_sel_hi:[1,0]
	v_pk_mul_f32 v[62:63], v[62:63], v[0:1] op_sel_hi:[1,0]
	v_pk_mul_f32 v[52:53], v[52:53], v[0:1] op_sel_hi:[1,0]
	v_pk_mul_f32 v[50:51], v[50:51], v[0:1] op_sel_hi:[1,0]
	v_pk_mul_f32 v[48:49], v[48:49], v[0:1] op_sel_hi:[1,0]
	v_pk_mul_f32 v[46:47], v[46:47], v[0:1] op_sel_hi:[1,0]
	v_pk_mul_f32 v[32:33], v[32:33], v[0:1] op_sel_hi:[1,0]
	v_pk_mul_f32 v[30:31], v[30:31], v[0:1] op_sel_hi:[1,0]
	v_cmp_gt_i32_e32 vcc, s4, v96
	s_waitcnt vmcnt(11) lgkmcnt(0)
	v_pk_mul_f32 v[62:63], v[102:103], v[62:63]
	v_pk_mul_f32 v[64:65], v[104:105], v[64:65]
	s_waitcnt vmcnt(10) lgkmcnt(0)
	v_pk_add_f32 v[102:103], v[116:117], 1.0 op_sel_hi:[1,0]
	v_pk_add_f32 v[104:105], v[114:115], 1.0 op_sel_hi:[1,0]
	s_waitcnt vmcnt(9) lgkmcnt(0)
	v_pk_fma_f32 v[64:65], v[102:103], v[64:65], v[120:121]
	v_pk_fma_f32 v[62:63], v[104:105], v[62:63], v[118:119]
	v_lshl_add_u64 v[102:103], v[98:99], 0, v[86:87]
	v_cvt_pk_bf16_f32 v62, v62, v63
	v_cvt_pk_bf16_f32 v63, v64, v65
	global_store_dwordx2 v[82:83], v[62:63], off nt
	s_waitcnt vmcnt(7) lgkmcnt(0)
	v_pk_mul_f32 v[50:51], v[168:169], v[50:51]
	v_pk_mul_f32 v[52:53], v[170:171], v[52:53]
	v_pk_add_f32 v[62:63], v[174:175], 1.0 op_sel_hi:[1, 0]
	v_pk_add_f32 v[64:65], v[172:173], 1.0 op_sel_hi:[1, 0]
	v_pk_fma_f32 v[52:53], v[62:63], v[52:53], v[178:179]
	v_pk_fma_f32 v[50:51], v[64:65], v[50:51], v[176:177]
	v_lshl_add_u64 v[62:63], v[98:99], 0, v[88:89]
	v_cvt_pk_bf16_f32 v50, v50, v51
	v_cvt_pk_bf16_f32 v51, v52, v53
	global_store_dwordx2 v[82:83], v[50:51], off offset:512 nt
	s_waitcnt vmcnt(5) lgkmcnt(0)
	v_pk_mul_f32 v[46:47], v[180:181], v[46:47]
	v_pk_mul_f32 v[48:49], v[182:183], v[48:49]
	v_pk_add_f32 v[50:51], v[186:187], 1.0 op_sel_hi:[1, 0]
	v_pk_add_f32 v[52:53], v[184:185], 1.0 op_sel_hi:[1, 0]
	v_pk_fma_f32 v[48:49], v[50:51], v[48:49], v[190:191]
	v_pk_fma_f32 v[46:47], v[52:53], v[46:47], v[188:189]
	v_lshl_add_u64 v[50:51], v[98:99], 0, v[90:91]
	v_cvt_pk_bf16_f32 v46, v46, v47
	v_cvt_pk_bf16_f32 v47, v48, v49
	global_store_dwordx2 v[82:83], v[46:47], off offset:1024 nt
	s_waitcnt vmcnt(3) lgkmcnt(0)
	v_pk_mul_f32 v[30:31], v[30:31], v[192:193]
	v_pk_mul_f32 v[32:33], v[32:33], v[194:195]
	v_pk_add_f32 v[46:47], v[198:199], 1.0 op_sel_hi:[1, 0]
	v_pk_add_f32 v[48:49], v[196:197], 1.0 op_sel_hi:[1, 0]
	v_pk_fma_f32 v[32:33], v[32:33], v[46:47], v[202:203]
	v_pk_fma_f32 v[30:31], v[30:31], v[48:49], v[200:201]
	s_nop 0
	v_cvt_pk_bf16_f32 v30, v30, v31
	v_cvt_pk_bf16_f32 v31, v32, v33
	global_store_dwordx2 v[82:83], v[30:31], off offset:1536 nt
	s_and_saveexec_b64 s[36:37], vcc
	s_cbranch_execz .LBB0_478
	v_mul_f32_e32 v0, v59, v59
	v_mul_f32_e32 v30, v43, v43
	v_fmac_f32_e32 v0, v58, v58
	v_fmac_f32_e32 v30, v42, v42
	v_fmac_f32_e32 v0, v60, v60
	v_fmac_f32_e32 v30, v44, v44
	v_fmac_f32_e32 v0, v61, v61
	v_fmac_f32_e32 v30, v45, v45
	v_add_f32_e32 v0, v30, v0
	v_mul_f32_e32 v30, v39, v39
	v_fmac_f32_e32 v30, v38, v38
	v_fmac_f32_e32 v30, v40, v40
	v_fmac_f32_e32 v30, v41, v41
	v_add_f32_e32 v0, v30, v0
	v_mul_f32_e32 v30, v35, v35
	v_fmac_f32_e32 v30, v34, v34
	v_fmac_f32_e32 v30, v36, v36
	v_fmac_f32_e32 v30, v37, v37
	v_add_f32_e32 v0, v30, v0
	ds_bpermute_b32 v46, v108, v0
	v_min_i32_e32 v30, 0x8000, v96
	v_ashrrev_i32_e32 v30, 12, v30
	v_lshl_add_u32 v222, v30, 13, v223
	v_mul_i32_i24_e32 v30, 0x1800, v30
	v_ashrrev_i32_e32 v31, 31, v30
	s_waitcnt lgkmcnt(0)
	v_add_f32_e32 v0, v0, v46
	ds_bpermute_b32 v46, v109, v0
	v_lshl_add_u64 v[32:33], v[30:31], 2, s[22:23]
	v_lshl_add_u64 v[30:31], v[32:33], 0, s[10:11]
	v_lshl_add_u64 v[52:53], v[30:31], 0, v[84:85]
	v_ashrrev_i32_e32 v97, 31, v96
	s_waitcnt lgkmcnt(0)
	v_add_f32_e32 v0, v0, v46
	ds_bpermute_b32 v46, v110, v0
	ds_read_b128 v[48:51], v242
	ds_read_b128 v[62:65], v222 offset:4096
	v_lshl_add_u64 v[32:33], v[32:33], 0, v[84:85]
	s_waitcnt lgkmcnt(0)
	v_add_f32_e32 v0, v0, v46
	ds_bpermute_b32 v46, v111, v0
	s_waitcnt lgkmcnt(0)
	v_add_f32_e32 v0, v0, v46
	ds_bpermute_b32 v46, v112, v0
	s_waitcnt lgkmcnt(0)
	v_add_f32_e32 v0, v0, v46
	ds_bpermute_b32 v46, v113, v0
	s_waitcnt lgkmcnt(0)
	v_add_f32_e32 v0, v0, v46
	v_fmamk_f32 v0, v0, 0x3a800000, v218
	v_cmp_gt_f32_e32 vcc, s13, v0
	v_mul_f32_e32 v46, 0x4b800000, v0
	s_nop 0
	v_cndmask_b32_e32 v0, v0, v46, vcc
	v_rsq_f32_e32 v0, v0
	s_nop 0
	v_mul_f32_e32 v46, 0x45800000, v0
	v_cndmask_b32_e32 v0, v0, v46, vcc
	v_lshlrev_b64 v[46:47], 11, v[96:97]
	ds_read_b128 v[96:99], v222
	v_mov_b32_e32 v87, v1
	v_mov_b32_e32 v89, v1
	v_mov_b32_e32 v91, v1
	ds_read_b128 v[168:171], v242 offset:1024
	v_lshl_add_u64 v[172:173], v[30:31], 0, v[86:87]
	ds_read_b128 v[172:175], v222 offset:5120
	ds_read_b128 v[176:179], v222 offset:1024
	ds_read_b128 v[180:183], v242 offset:2048
	v_lshl_add_u64 v[184:185], v[30:31], 0, v[88:89]
	ds_read_b128 v[184:187], v222 offset:6144
	ds_read_b128 v[188:191], v222 offset:2048
	ds_read_b128 v[192:195], v242 offset:3072
	v_lshl_add_u64 v[196:197], v[30:31], 0, v[90:91]
	ds_read_b128 v[196:199], v222 offset:7168
	ds_read_b128 v[200:203], v222 offset:3072
	v_pk_mul_f32 v[52:53], v[60:61], v[0:1] op_sel_hi:[1,0]
	v_pk_mul_f32 v[58:59], v[58:59], v[0:1] op_sel_hi:[1,0]
	v_pk_mul_f32 v[44:45], v[44:45], v[0:1] op_sel_hi:[1,0]
	v_pk_mul_f32 v[42:43], v[42:43], v[0:1] op_sel_hi:[1,0]
	v_pk_mul_f32 v[40:41], v[40:41], v[0:1] op_sel_hi:[1,0]
	v_pk_mul_f32 v[38:39], v[38:39], v[0:1] op_sel_hi:[1,0]
	v_pk_mul_f32 v[36:37], v[36:37], v[0:1] op_sel_hi:[1,0]
	v_pk_mul_f32 v[34:35], v[34:35], v[0:1] op_sel_hi:[1,0]
	s_waitcnt vmcnt(11) lgkmcnt(0)
	v_pk_mul_f32 v[48:49], v[48:49], v[58:59]
	v_pk_mul_f32 v[50:51], v[50:51], v[52:53]
	s_waitcnt vmcnt(10) lgkmcnt(0)
	v_pk_add_f32 v[52:53], v[64:65], 1.0 op_sel_hi:[1,0]
	v_pk_add_f32 v[58:59], v[62:63], 1.0 op_sel_hi:[1,0]
	v_lshl_add_u64 v[62:63], v[80:81], 0, v[46:47]
	s_waitcnt vmcnt(9) lgkmcnt(0)
	v_pk_fma_f32 v[50:51], v[52:53], v[50:51], v[98:99]
	v_pk_fma_f32 v[48:49], v[58:59], v[48:49], v[96:97]
	s_nop 0
	v_cvt_pk_bf16_f32 v48, v48, v49
	v_cvt_pk_bf16_f32 v49, v50, v51
	global_store_dwordx2 v[62:63], v[48:49], off nt
	v_lshl_add_u64 v[50:51], v[30:31], 0, v[86:87]
	s_waitcnt vmcnt(7) lgkmcnt(0)
	v_pk_mul_f32 v[42:43], v[168:169], v[42:43]
	v_pk_mul_f32 v[44:45], v[170:171], v[44:45]
	v_pk_add_f32 v[46:47], v[174:175], 1.0 op_sel_hi:[1, 0]
	v_pk_add_f32 v[48:49], v[172:173], 1.0 op_sel_hi:[1, 0]
	v_pk_fma_f32 v[44:45], v[46:47], v[44:45], v[178:179]
	v_pk_fma_f32 v[42:43], v[48:49], v[42:43], v[176:177]
	v_lshl_add_u64 v[46:47], v[30:31], 0, v[88:89]
	v_cvt_pk_bf16_f32 v42, v42, v43
	v_cvt_pk_bf16_f32 v43, v44, v45
	global_store_dwordx2 v[62:63], v[42:43], off offset:512 nt
	v_lshl_add_u64 v[30:31], v[30:31], 0, v[90:91]
	s_waitcnt vmcnt(5) lgkmcnt(0)
	v_pk_mul_f32 v[38:39], v[180:181], v[38:39]
	v_pk_mul_f32 v[40:41], v[182:183], v[40:41]
	v_pk_add_f32 v[42:43], v[186:187], 1.0 op_sel_hi:[1, 0]
	v_pk_add_f32 v[44:45], v[184:185], 1.0 op_sel_hi:[1, 0]
	v_pk_fma_f32 v[40:41], v[42:43], v[40:41], v[190:191]
	v_pk_fma_f32 v[38:39], v[44:45], v[38:39], v[188:189]
	s_nop 0
	v_cvt_pk_bf16_f32 v38, v38, v39
	v_cvt_pk_bf16_f32 v39, v40, v41
	global_store_dwordx2 v[62:63], v[38:39], off offset:1024 nt
	s_waitcnt vmcnt(3) lgkmcnt(0)
	v_pk_mul_f32 v[34:35], v[34:35], v[192:193]
	v_pk_mul_f32 v[36:37], v[36:37], v[194:195]
	v_pk_add_f32 v[38:39], v[198:199], 1.0 op_sel_hi:[1, 0]
	v_pk_add_f32 v[40:41], v[196:197], 1.0 op_sel_hi:[1, 0]
	v_pk_fma_f32 v[32:33], v[36:37], v[38:39], v[202:203]
	v_pk_fma_f32 v[30:31], v[34:35], v[40:41], v[200:201]
	s_nop 0
	v_cvt_pk_bf16_f32 v30, v30, v31
	v_cvt_pk_bf16_f32 v31, v32, v33
	global_store_dwordx2 v[62:63], v[30:31], off offset:1536 nt
	s_or_b64 exec, exec, s[36:37]
	v_cmp_gt_i32_e32 vcc, s4, v94
	s_and_saveexec_b64 s[36:37], vcc
	s_cbranch_execnz .LBB0_479

.LBB0_479:
	v_mul_f32_e32 v0, v55, v55
	v_mul_f32_e32 v30, v27, v27
	v_fmac_f32_e32 v0, v54, v54
	v_fmac_f32_e32 v30, v26, v26
	v_fmac_f32_e32 v0, v56, v56
	v_fmac_f32_e32 v30, v28, v28
	v_fmac_f32_e32 v0, v57, v57
	v_fmac_f32_e32 v30, v29, v29
	v_add_f32_e32 v0, v30, v0
	v_mul_f32_e32 v30, v19, v19
	v_fmac_f32_e32 v30, v18, v18
	v_fmac_f32_e32 v30, v20, v20
	v_fmac_f32_e32 v30, v21, v21
	v_add_f32_e32 v0, v30, v0
	v_mul_f32_e32 v30, v15, v15
	v_fmac_f32_e32 v30, v14, v14
	v_fmac_f32_e32 v30, v16, v16
	v_fmac_f32_e32 v30, v17, v17
	v_add_f32_e32 v0, v30, v0
	v_min_i32_e32 v30, 0x8000, v94
	v_ashrrev_i32_e32 v30, 12, v30
	v_lshl_add_u32 v222, v30, 13, v223
	v_mul_i32_i24_e32 v30, 0x1800, v30
	v_ashrrev_i32_e32 v31, 31, v30
	v_lshl_add_u64 v[36:37], v[30:31], 2, s[22:23]
	ds_bpermute_b32 v30, v108, v0
	v_lshl_add_u64 v[34:35], v[36:37], 0, s[10:11]
	v_mov_b32_e32 v85, v1
	v_lshl_add_u64 v[38:39], v[34:35], 0, v[84:85]
	ds_read_b128 v[40:43], v222 offset:4096
	s_waitcnt lgkmcnt(0)
	v_add_f32_e32 v0, v0, v30
	ds_bpermute_b32 v30, v109, v0
	v_lshl_add_u64 v[38:39], v[36:37], 0, v[84:85]
	ds_read_b128 v[44:47], v222
	v_ashrrev_i32_e32 v95, 31, v94
	v_lshlrev_b64 v[48:49], 11, v[94:95]
	s_waitcnt lgkmcnt(0)
	v_add_f32_e32 v0, v0, v30
	ds_bpermute_b32 v30, v110, v0
	v_mov_b32_e32 v87, v1
	v_mov_b32_e32 v89, v1
	v_mov_b32_e32 v91, v1
	s_waitcnt lgkmcnt(0)
	v_add_f32_e32 v0, v0, v30
	ds_bpermute_b32 v30, v111, v0
	s_waitcnt lgkmcnt(0)
	v_add_f32_e32 v0, v0, v30
	ds_bpermute_b32 v30, v112, v0
	s_waitcnt lgkmcnt(0)
	v_add_f32_e32 v0, v0, v30
	ds_bpermute_b32 v30, v113, v0
	s_waitcnt lgkmcnt(0)
	v_add_f32_e32 v0, v0, v30
	v_fmamk_f32 v0, v0, 0x3a800000, v218
	v_cmp_gt_f32_e32 vcc, s13, v0
	v_mul_f32_e32 v30, 0x4b800000, v0
	s_waitcnt vmcnt(1) lgkmcnt(0)
	v_pk_add_f32 v[40:41], v[40:41], 1.0 op_sel_hi:[1,0]
	v_cndmask_b32_e32 v0, v0, v30, vcc
	v_rsq_f32_e32 v0, v0
	s_nop 0
	v_mul_f32_e32 v30, 0x45800000, v0
	v_cndmask_b32_e32 v0, v0, v30, vcc
	ds_read_b128 v[30:33], v242
	v_mov_b32_e32 v87, v1
	v_mov_b32_e32 v89, v1
	v_mov_b32_e32 v91, v1
	ds_read_b128 v[168:171], v242 offset:1024
	v_lshl_add_u64 v[172:173], v[34:35], 0, v[86:87]
	ds_read_b128 v[172:175], v222 offset:5120
	ds_read_b128 v[176:179], v222 offset:1024
	ds_read_b128 v[180:183], v242 offset:2048
	v_lshl_add_u64 v[184:185], v[34:35], 0, v[88:89]
	ds_read_b128 v[184:187], v222 offset:6144
	ds_read_b128 v[188:191], v222 offset:2048
	ds_read_b128 v[192:195], v242 offset:3072
	v_lshl_add_u64 v[196:197], v[34:35], 0, v[90:91]
	ds_read_b128 v[196:199], v222 offset:7168
	ds_read_b128 v[200:203], v222 offset:3072
	v_pk_mul_f32 v[36:37], v[56:57], v[0:1] op_sel_hi:[1,0]
	v_pk_mul_f32 v[50:51], v[54:55], v[0:1] op_sel_hi:[1,0]
	v_pk_mul_f32 v[28:29], v[28:29], v[0:1] op_sel_hi:[1,0]
	v_pk_mul_f32 v[26:27], v[26:27], v[0:1] op_sel_hi:[1,0]
	v_pk_mul_f32 v[20:21], v[20:21], v[0:1] op_sel_hi:[1,0]
	v_pk_mul_f32 v[18:19], v[18:19], v[0:1] op_sel_hi:[1,0]
	v_pk_mul_f32 v[16:17], v[16:17], v[0:1] op_sel_hi:[1,0]
	v_pk_mul_f32 v[14:15], v[14:15], v[0:1] op_sel_hi:[1,0]
	s_waitcnt vmcnt(9) lgkmcnt(0)
	v_pk_mul_f32 v[30:31], v[30:31], v[50:51]
	v_pk_mul_f32 v[32:33], v[32:33], v[36:37]
	v_pk_add_f32 v[36:37], v[42:43], 1.0 op_sel_hi:[1,0]
	v_pk_fma_f32 v[30:31], v[40:41], v[30:31], v[44:45]
	v_pk_fma_f32 v[32:33], v[36:37], v[32:33], v[46:47]
	v_cvt_pk_bf16_f32 v30, v30, v31
	v_cvt_pk_bf16_f32 v31, v32, v33
	v_lshl_add_u64 v[36:37], v[80:81], 0, v[48:49]
	global_store_dwordx2 v[36:37], v[30:31], off nt
	v_lshl_add_u64 v[40:41], v[34:35], 0, v[86:87]
	s_waitcnt vmcnt(7) lgkmcnt(0)
	v_pk_mul_f32 v[26:27], v[168:169], v[26:27]
	v_pk_mul_f32 v[28:29], v[170:171], v[28:29]
	v_pk_add_f32 v[30:31], v[174:175], 1.0 op_sel_hi:[1, 0]
	v_pk_add_f32 v[32:33], v[172:173], 1.0 op_sel_hi:[1, 0]
	v_pk_fma_f32 v[28:29], v[30:31], v[28:29], v[178:179]
	v_pk_fma_f32 v[26:27], v[32:33], v[26:27], v[176:177]
	v_lshl_add_u64 v[30:31], v[34:35], 0, v[88:89]
	v_cvt_pk_bf16_f32 v26, v26, v27
	v_cvt_pk_bf16_f32 v27, v28, v29
	global_store_dwordx2 v[36:37], v[26:27], off offset:512 nt
	s_waitcnt vmcnt(5) lgkmcnt(0)
	v_pk_mul_f32 v[18:19], v[180:181], v[18:19]
	v_pk_mul_f32 v[20:21], v[182:183], v[20:21]
	v_pk_add_f32 v[26:27], v[186:187], 1.0 op_sel_hi:[1, 0]
	v_pk_add_f32 v[28:29], v[184:185], 1.0 op_sel_hi:[1, 0]
	v_pk_fma_f32 v[20:21], v[26:27], v[20:21], v[190:191]
	v_pk_fma_f32 v[18:19], v[28:29], v[18:19], v[188:189]
	v_lshl_add_u64 v[26:27], v[34:35], 0, v[90:91]
	v_cvt_pk_bf16_f32 v18, v18, v19
	v_cvt_pk_bf16_f32 v19, v20, v21
	global_store_dwordx2 v[36:37], v[18:19], off offset:1024 nt
	s_waitcnt vmcnt(3) lgkmcnt(0)
	v_pk_mul_f32 v[14:15], v[14:15], v[192:193]
	v_pk_mul_f32 v[16:17], v[16:17], v[194:195]
	v_pk_add_f32 v[18:19], v[198:199], 1.0 op_sel_hi:[1, 0]
	v_pk_add_f32 v[20:21], v[196:197], 1.0 op_sel_hi:[1, 0]
	v_pk_fma_f32 v[16:17], v[16:17], v[18:19], v[202:203]
	v_pk_fma_f32 v[14:15], v[14:15], v[20:21], v[200:201]
	s_nop 0
	v_cvt_pk_bf16_f32 v14, v14, v15
	v_cvt_pk_bf16_f32 v15, v16, v17
	global_store_dwordx2 v[36:37], v[14:15], off offset:1536 nt
	s_or_b64 exec, exec, s[36:37]
	v_cmp_gt_i32_e32 vcc, s4, v92
	s_and_saveexec_b64 s[36:37], vcc
	s_cbranch_execz .LBB0_442
.LBB0_480:
	v_mul_f32_e32 v0, v23, v23
	v_mul_f32_e32 v14, v11, v11
	v_fmac_f32_e32 v0, v22, v22
	v_fmac_f32_e32 v14, v10, v10
	v_fmac_f32_e32 v0, v24, v24
	v_fmac_f32_e32 v14, v12, v12
	v_fmac_f32_e32 v0, v25, v25
	v_fmac_f32_e32 v14, v13, v13
	v_add_f32_e32 v0, v14, v0
	v_mul_f32_e32 v14, v7, v7
	v_fmac_f32_e32 v14, v6, v6
	v_fmac_f32_e32 v14, v8, v8
	v_fmac_f32_e32 v14, v9, v9
	v_add_f32_e32 v0, v14, v0
	v_mul_f32_e32 v14, v3, v3
	v_fmac_f32_e32 v14, v2, v2
	v_fmac_f32_e32 v14, v4, v4
	v_fmac_f32_e32 v14, v5, v5
	v_add_f32_e32 v0, v14, v0
	v_min_i32_e32 v14, 0x8000, v92
	v_ashrrev_i32_e32 v14, 12, v14
	v_lshl_add_u32 v222, v14, 13, v223
	v_mul_i32_i24_e32 v14, 0x1800, v14
	v_ashrrev_i32_e32 v15, 31, v14
	v_lshl_add_u64 v[20:21], v[14:15], 2, s[22:23]
	ds_bpermute_b32 v14, v108, v0
	v_lshl_add_u64 v[18:19], v[20:21], 0, s[10:11]
	v_mov_b32_e32 v85, v1
	v_lshl_add_u64 v[26:27], v[18:19], 0, v[84:85]
	ds_read_b128 v[28:31], v222 offset:4096
	s_waitcnt lgkmcnt(0)
	v_add_f32_e32 v0, v0, v14
	ds_bpermute_b32 v14, v109, v0
	v_lshl_add_u64 v[26:27], v[20:21], 0, v[84:85]
	ds_read_b128 v[32:35], v222
	v_ashrrev_i32_e32 v93, 31, v92
	v_lshlrev_b64 v[36:37], 11, v[92:93]
	s_waitcnt lgkmcnt(0)
	v_add_f32_e32 v0, v0, v14
	ds_bpermute_b32 v14, v110, v0
	v_mov_b32_e32 v87, v1
	v_mov_b32_e32 v89, v1
	v_mov_b32_e32 v91, v1
	s_waitcnt lgkmcnt(0)
	v_add_f32_e32 v0, v0, v14
	ds_bpermute_b32 v14, v111, v0
	s_waitcnt lgkmcnt(0)
	v_add_f32_e32 v0, v0, v14
	ds_bpermute_b32 v14, v112, v0
	s_waitcnt lgkmcnt(0)
	v_add_f32_e32 v0, v0, v14
	ds_bpermute_b32 v14, v113, v0
	s_waitcnt lgkmcnt(0)
	v_add_f32_e32 v0, v0, v14
	v_fmamk_f32 v0, v0, 0x3a800000, v218
	v_cmp_gt_f32_e32 vcc, s13, v0
	v_mul_f32_e32 v14, 0x4b800000, v0
	s_nop 0
	v_cndmask_b32_e32 v0, v0, v14, vcc
	v_rsq_f32_e32 v0, v0
	s_nop 0
	v_mul_f32_e32 v14, 0x45800000, v0
	v_cndmask_b32_e32 v0, v0, v14, vcc
	ds_read_b128 v[14:17], v242
	v_mov_b32_e32 v87, v1
	v_mov_b32_e32 v89, v1
	v_mov_b32_e32 v91, v1
	ds_read_b128 v[168:171], v242 offset:1024
	v_lshl_add_u64 v[172:173], v[18:19], 0, v[86:87]
	ds_read_b128 v[172:175], v222 offset:5120
	ds_read_b128 v[176:179], v222 offset:1024
	ds_read_b128 v[180:183], v242 offset:2048
	v_lshl_add_u64 v[184:185], v[18:19], 0, v[88:89]
	ds_read_b128 v[184:187], v222 offset:6144
	ds_read_b128 v[188:191], v222 offset:2048
	ds_read_b128 v[192:195], v242 offset:3072
	v_lshl_add_u64 v[196:197], v[18:19], 0, v[90:91]
	ds_read_b128 v[196:199], v222 offset:7168
	ds_read_b128 v[200:203], v222 offset:3072
	v_pk_mul_f32 v[20:21], v[24:25], v[0:1] op_sel_hi:[1,0]
	v_pk_mul_f32 v[22:23], v[22:23], v[0:1] op_sel_hi:[1,0]
	v_pk_mul_f32 v[12:13], v[12:13], v[0:1] op_sel_hi:[1,0]
	v_pk_mul_f32 v[10:11], v[10:11], v[0:1] op_sel_hi:[1,0]
	v_pk_mul_f32 v[8:9], v[8:9], v[0:1] op_sel_hi:[1,0]
	v_pk_mul_f32 v[6:7], v[6:7], v[0:1] op_sel_hi:[1,0]
	v_pk_mul_f32 v[4:5], v[4:5], v[0:1] op_sel_hi:[1,0]
	v_pk_mul_f32 v[2:3], v[2:3], v[0:1] op_sel_hi:[1,0]
	s_waitcnt vmcnt(9) lgkmcnt(0)
	v_pk_mul_f32 v[14:15], v[14:15], v[22:23]
	v_pk_mul_f32 v[16:17], v[16:17], v[20:21]
	v_pk_add_f32 v[20:21], v[30:31], 1.0 op_sel_hi:[1,0]
	v_pk_add_f32 v[22:23], v[28:29], 1.0 op_sel_hi:[1,0]
	v_pk_fma_f32 v[16:17], v[20:21], v[16:17], v[34:35]
	v_pk_fma_f32 v[14:15], v[22:23], v[14:15], v[32:33]
	v_lshl_add_u64 v[20:21], v[80:81], 0, v[36:37]
	v_cvt_pk_bf16_f32 v14, v14, v15
	v_cvt_pk_bf16_f32 v15, v16, v17
	global_store_dwordx2 v[20:21], v[14:15], off nt
	v_lshl_add_u64 v[22:23], v[18:19], 0, v[86:87]
	s_waitcnt vmcnt(7) lgkmcnt(0)
	v_pk_mul_f32 v[10:11], v[168:169], v[10:11]
	v_pk_mul_f32 v[12:13], v[170:171], v[12:13]
	v_pk_add_f32 v[14:15], v[174:175], 1.0 op_sel_hi:[1, 0]
	v_pk_add_f32 v[16:17], v[172:173], 1.0 op_sel_hi:[1, 0]
	v_pk_fma_f32 v[12:13], v[14:15], v[12:13], v[178:179]
	v_pk_fma_f32 v[10:11], v[16:17], v[10:11], v[176:177]
	v_lshl_add_u64 v[14:15], v[18:19], 0, v[88:89]
	v_cvt_pk_bf16_f32 v10, v10, v11
	v_cvt_pk_bf16_f32 v11, v12, v13
	global_store_dwordx2 v[20:21], v[10:11], off offset:512 nt
	s_waitcnt vmcnt(5) lgkmcnt(0)
	v_pk_mul_f32 v[6:7], v[180:181], v[6:7]
	v_pk_mul_f32 v[8:9], v[182:183], v[8:9]
	v_pk_add_f32 v[10:11], v[186:187], 1.0 op_sel_hi:[1, 0]
	v_pk_add_f32 v[12:13], v[184:185], 1.0 op_sel_hi:[1, 0]
	v_pk_fma_f32 v[8:9], v[10:11], v[8:9], v[190:191]
	v_pk_fma_f32 v[6:7], v[12:13], v[6:7], v[188:189]
	v_lshl_add_u64 v[10:11], v[18:19], 0, v[90:91]
	v_cvt_pk_bf16_f32 v6, v6, v7
	v_cvt_pk_bf16_f32 v7, v8, v9
	global_store_dwordx2 v[20:21], v[6:7], off offset:1024 nt
	s_waitcnt vmcnt(3) lgkmcnt(0)
	v_pk_mul_f32 v[2:3], v[2:3], v[192:193]
	v_pk_mul_f32 v[4:5], v[4:5], v[194:195]
	v_pk_add_f32 v[6:7], v[198:199], 1.0 op_sel_hi:[1, 0]
	v_pk_add_f32 v[8:9], v[196:197], 1.0 op_sel_hi:[1, 0]
	v_pk_fma_f32 v[4:5], v[4:5], v[6:7], v[202:203]
	v_pk_fma_f32 v[2:3], v[2:3], v[8:9], v[200:201]
	s_nop 0
	v_cvt_pk_bf16_f32 v2, v2, v3
	v_cvt_pk_bf16_f32 v3, v4, v5
	global_store_dwordx2 v[20:21], v[2:3], off offset:1536 nt
	s_branch .LBB0_442
	s_nop 0
	s_nop 0
	s_nop 0
	s_nop 0
	s_nop 0
	s_nop 0
	s_nop 0
	s_nop 0
	s_nop 0
	s_nop 0
	s_nop 0
	s_nop 0
	s_nop 0
	s_nop 0
	s_nop 0
	s_nop 0
	s_nop 0
	s_nop 0
	s_nop 0
	s_nop 0
	s_nop 0
	s_nop 0
	s_nop 0
	s_nop 0
	s_nop 0
	s_nop 0
	s_nop 0
	s_nop 0
	s_nop 0
	s_nop 0
	s_nop 0
	s_nop 0
	s_nop 0
	s_nop 0
	s_nop 0
	s_nop 0
	s_nop 0
	s_nop 0
	s_nop 0
	s_nop 0
	s_nop 0
	s_nop 0
	s_nop 0
	s_nop 0
	s_nop 0
	s_nop 0
	s_nop 0
	s_nop 0
	s_nop 0
	s_nop 0
	s_nop 0
	s_nop 0
	s_nop 0
	s_nop 0
	s_nop 0
	s_nop 0
	s_nop 0
	s_nop 0
	s_nop 0
	s_nop 0
	s_nop 0
	s_nop 0
	s_nop 0
	s_nop 0
	s_nop 0
	s_nop 0
	s_nop 0
	s_nop 0
	s_nop 0
	s_nop 0
	s_nop 0
	s_nop 0
	s_nop 0
	s_nop 0
	s_nop 0
	s_nop 0

.LBB0_562:
	s_or_b64 exec, exec, s[34:35]
	v_min_i32_e32 v0, 0x8000, v66
	v_ashrrev_i32_e32 v0, 12, v0
	v_lshl_add_u32 v222, v0, 13, v223
	v_mul_i32_i24_e32 v92, 0x1800, v0
	v_ashrrev_i32_e32 v93, 31, v92
	v_lshl_add_u64 v[100:101], v[92:93], 2, s[44:45]
	s_mov_b64 s[8:9], 0x1000
	v_lshl_add_u64 v[112:113], v[100:101], 0, s[8:9]
	v_mov_b32_e32 v79, v1
	v_lshl_add_u64 v[96:97], v[112:113], 0, v[78:79]
	ds_read_b128 v[92:95], v242
	v_lshl_add_u64 v[100:101], v[100:101], 0, v[78:79]
	ds_read_b128 v[96:99], v222 offset:4096
	s_waitcnt vmcnt(0) lgkmcnt(0)
	v_mul_f32_e32 v0, v39, v39
	ds_read_b128 v[108:111], v222
	v_mov_b32_e32 v81, v1
	v_mov_b32_e32 v83, v1
	v_mov_b32_e32 v85, v1
	ds_read_b128 v[168:171], v242 offset:1024
	v_lshl_add_u64 v[172:173], v[112:113], 0, v[80:81]
	ds_read_b128 v[172:175], v222 offset:5120
	ds_read_b128 v[176:179], v222 offset:1024
	ds_read_b128 v[180:183], v242 offset:2048
	v_lshl_add_u64 v[184:185], v[112:113], 0, v[82:83]
	ds_read_b128 v[184:187], v222 offset:6144
	ds_read_b128 v[188:191], v222 offset:2048
	ds_read_b128 v[192:195], v242 offset:3072
	v_lshl_add_u64 v[196:197], v[112:113], 0, v[84:85]
	ds_read_b128 v[196:199], v222 offset:7168
	ds_read_b128 v[200:203], v222 offset:3072
	v_mul_f32_e32 v81, v23, v23
	v_mul_f32_e32 v83, v7, v7
	v_fmac_f32_e32 v0, v38, v38
	v_fmac_f32_e32 v81, v22, v22
	v_mul_f32_e32 v85, v3, v3
	v_fmac_f32_e32 v83, v6, v6
	v_fmac_f32_e32 v0, v40, v40
	v_fmac_f32_e32 v81, v24, v24
	v_fmac_f32_e32 v85, v2, v2
	v_fmac_f32_e32 v83, v8, v8
	v_fmac_f32_e32 v0, v41, v41
	v_fmac_f32_e32 v81, v25, v25
	v_fmac_f32_e32 v85, v4, v4
	v_fmac_f32_e32 v83, v9, v9
	v_add_f32_e32 v0, v81, v0
	v_fmac_f32_e32 v85, v5, v5
	v_add_f32_e32 v0, v83, v0
	v_add_f32_e32 v0, v85, v0
	ds_bpermute_b32 v81, v102, v0
	v_mov_b32_e32 v85, v1
	s_waitcnt lgkmcnt(0)
	v_add_f32_e32 v0, v0, v81
	ds_bpermute_b32 v81, v103, v0
	s_waitcnt lgkmcnt(0)
	v_add_f32_e32 v0, v0, v81
	ds_bpermute_b32 v81, v104, v0
	s_waitcnt lgkmcnt(0)
	v_add_f32_e32 v0, v0, v81
	ds_bpermute_b32 v81, v105, v0
	s_waitcnt lgkmcnt(0)
	v_add_f32_e32 v0, v0, v81
	ds_bpermute_b32 v81, v106, v0
	s_waitcnt lgkmcnt(0)
	v_add_f32_e32 v0, v0, v81
	ds_bpermute_b32 v81, v107, v0
	s_waitcnt lgkmcnt(0)
	v_add_f32_e32 v0, v0, v81
	v_fmamk_f32 v0, v0, 0x3a800000, v218
	v_mul_f32_e32 v81, 0x4b800000, v0
	v_cmp_gt_f32_e32 vcc, s13, v0
	s_nop 1
	v_cndmask_b32_e32 v0, v0, v81, vcc
	v_rsq_f32_e32 v0, v0
	v_mov_b32_e32 v81, v1
	v_mul_f32_e32 v83, 0x45800000, v0
	v_cndmask_b32_e32 v0, v0, v83, vcc
	v_pk_mul_f32 v[40:41], v[40:41], v[0:1] op_sel_hi:[1,0]
	v_pk_mul_f32 v[38:39], v[38:39], v[0:1] op_sel_hi:[1,0]
	v_pk_mul_f32 v[24:25], v[24:25], v[0:1] op_sel_hi:[1,0]
	v_pk_mul_f32 v[22:23], v[22:23], v[0:1] op_sel_hi:[1,0]
	v_mov_b32_e32 v83, v1
	v_pk_mul_f32 v[8:9], v[8:9], v[0:1] op_sel_hi:[1,0]
	v_pk_mul_f32 v[6:7], v[6:7], v[0:1] op_sel_hi:[1,0]
	v_pk_mul_f32 v[4:5], v[4:5], v[0:1] op_sel_hi:[1,0]
	v_pk_mul_f32 v[2:3], v[2:3], v[0:1] op_sel_hi:[1,0]
	v_pk_mul_f32 v[38:39], v[92:93], v[38:39]
	v_pk_mul_f32 v[40:41], v[94:95], v[40:41]
	v_pk_add_f32 v[92:93], v[98:99], 1.0 op_sel_hi:[1,0]
	v_pk_add_f32 v[94:95], v[96:97], 1.0 op_sel_hi:[1,0]
	s_waitcnt vmcnt(9) lgkmcnt(0)
	v_pk_fma_f32 v[40:41], v[92:93], v[40:41], v[110:111]
	v_pk_fma_f32 v[38:39], v[94:95], v[38:39], v[108:109]
	v_lshl_add_u64 v[92:93], v[112:113], 0, v[80:81]
	v_cvt_pk_bf16_f32 v38, v38, v39
	v_cvt_pk_bf16_f32 v39, v40, v41
	global_store_dwordx2 v[76:77], v[38:39], off nt
	v_cmp_gt_i32_e32 vcc, s15, v86
	s_waitcnt vmcnt(7) lgkmcnt(0)
	v_pk_mul_f32 v[22:23], v[168:169], v[22:23]
	v_pk_mul_f32 v[24:25], v[170:171], v[24:25]
	v_pk_add_f32 v[38:39], v[174:175], 1.0 op_sel_hi:[1, 0]
	v_pk_add_f32 v[40:41], v[172:173], 1.0 op_sel_hi:[1, 0]
	v_pk_fma_f32 v[24:25], v[38:39], v[24:25], v[178:179]
	v_pk_fma_f32 v[22:23], v[40:41], v[22:23], v[176:177]
	v_lshl_add_u64 v[38:39], v[112:113], 0, v[82:83]
	v_cvt_pk_bf16_f32 v22, v22, v23
	v_cvt_pk_bf16_f32 v23, v24, v25
	global_store_dwordx2 v[76:77], v[22:23], off offset:512 nt
	s_waitcnt vmcnt(5) lgkmcnt(0)
	v_pk_mul_f32 v[6:7], v[180:181], v[6:7]
	v_pk_mul_f32 v[8:9], v[182:183], v[8:9]
	v_pk_add_f32 v[22:23], v[186:187], 1.0 op_sel_hi:[1, 0]
	v_pk_add_f32 v[24:25], v[184:185], 1.0 op_sel_hi:[1, 0]
	v_pk_fma_f32 v[8:9], v[22:23], v[8:9], v[190:191]
	v_pk_fma_f32 v[6:7], v[24:25], v[6:7], v[188:189]
	v_lshl_add_u64 v[22:23], v[112:113], 0, v[84:85]
	v_cvt_pk_bf16_f32 v6, v6, v7
	v_cvt_pk_bf16_f32 v7, v8, v9
	global_store_dwordx2 v[76:77], v[6:7], off offset:1024 nt
	s_waitcnt vmcnt(3) lgkmcnt(0)
	v_pk_mul_f32 v[2:3], v[2:3], v[192:193]
	v_pk_mul_f32 v[4:5], v[4:5], v[194:195]
	v_pk_add_f32 v[6:7], v[198:199], 1.0 op_sel_hi:[1, 0]
	v_pk_add_f32 v[8:9], v[196:197], 1.0 op_sel_hi:[1, 0]
	v_pk_fma_f32 v[4:5], v[4:5], v[6:7], v[202:203]
	v_pk_fma_f32 v[2:3], v[2:3], v[8:9], v[200:201]
	s_nop 0
	v_cvt_pk_bf16_f32 v2, v2, v3
	v_cvt_pk_bf16_f32 v3, v4, v5
	global_store_dwordx2 v[76:77], v[2:3], off offset:1536 nt
	s_and_saveexec_b64 s[34:35], vcc
	s_cbranch_execz .LBB0_565
	v_min_i32_e32 v0, 0x8000, v86
	v_ashrrev_i32_e32 v0, 12, v0
	v_lshl_add_u32 v222, v0, 13, v223
	v_mul_i32_i24_e32 v2, 0x1800, v0
	v_ashrrev_i32_e32 v3, 31, v2
	v_lshl_add_u64 v[22:23], v[2:3], 2, s[44:45]
	v_lshl_add_u64 v[38:39], v[22:23], 0, s[8:9]
	v_lshl_add_u64 v[6:7], v[38:39], 0, v[78:79]
	ds_read_b128 v[2:5], v242
	v_lshl_add_u64 v[40:41], v[22:23], 0, v[78:79]
	ds_read_b128 v[6:9], v222 offset:4096
	v_mul_f32_e32 v0, v35, v35
	ds_read_b128 v[22:25], v222
	v_mov_b32_e32 v81, v1
	v_mov_b32_e32 v83, v1
	v_mov_b32_e32 v85, v1
	ds_read_b128 v[168:171], v242 offset:1024
	v_lshl_add_u64 v[172:173], v[38:39], 0, v[80:81]
	ds_read_b128 v[172:175], v222 offset:5120
	ds_read_b128 v[176:179], v222 offset:1024
	ds_read_b128 v[180:183], v242 offset:2048
	v_lshl_add_u64 v[184:185], v[38:39], 0, v[82:83]
	ds_read_b128 v[184:187], v222 offset:6144
	ds_read_b128 v[188:191], v222 offset:2048
	ds_read_b128 v[192:195], v242 offset:3072
	v_lshl_add_u64 v[196:197], v[38:39], 0, v[84:85]
	ds_read_b128 v[196:199], v222 offset:7168
	ds_read_b128 v[200:203], v222 offset:3072
	v_mul_f32_e32 v79, v31, v31
	v_mul_f32_e32 v87, v19, v19
	v_fmac_f32_e32 v0, v34, v34
	v_fmac_f32_e32 v79, v30, v30
	v_mul_f32_e32 v89, v11, v11
	v_fmac_f32_e32 v87, v18, v18
	v_fmac_f32_e32 v0, v36, v36
	v_fmac_f32_e32 v79, v32, v32
	v_fmac_f32_e32 v89, v10, v10
	v_fmac_f32_e32 v87, v20, v20
	v_fmac_f32_e32 v0, v37, v37
	v_fmac_f32_e32 v79, v33, v33
	v_fmac_f32_e32 v89, v12, v12
	v_fmac_f32_e32 v87, v21, v21
	v_add_f32_e32 v0, v79, v0
	v_fmac_f32_e32 v89, v13, v13
	v_add_f32_e32 v0, v87, v0
	v_add_f32_e32 v0, v89, v0
	ds_bpermute_b32 v79, v102, v0
	v_ashrrev_i32_e32 v87, 31, v86
	v_lshlrev_b64 v[86:87], 11, v[86:87]
	v_lshl_add_u64 v[86:87], v[74:75], 0, v[86:87]
	s_waitcnt lgkmcnt(0)
	v_add_f32_e32 v0, v0, v79
	ds_bpermute_b32 v79, v103, v0
	s_waitcnt lgkmcnt(0)
	v_add_f32_e32 v0, v0, v79
	ds_bpermute_b32 v79, v104, v0
	s_waitcnt lgkmcnt(0)
	v_add_f32_e32 v0, v0, v79
	ds_bpermute_b32 v79, v105, v0
	s_waitcnt lgkmcnt(0)
	v_add_f32_e32 v0, v0, v79
	ds_bpermute_b32 v79, v106, v0
	s_waitcnt lgkmcnt(0)
	v_add_f32_e32 v0, v0, v79
	ds_bpermute_b32 v79, v107, v0
	s_waitcnt lgkmcnt(0)
	v_add_f32_e32 v0, v0, v79
	v_fmamk_f32 v0, v0, 0x3a800000, v218
	v_mul_f32_e32 v79, 0x4b800000, v0
	v_cmp_gt_f32_e32 vcc, s13, v0
	s_waitcnt vmcnt(10) lgkmcnt(0)
	v_pk_add_f32 v[8:9], v[8:9], 1.0 op_sel_hi:[1,0]
	v_cndmask_b32_e32 v0, v0, v79, vcc
	v_rsq_f32_e32 v0, v0
	v_pk_add_f32 v[6:7], v[6:7], 1.0 op_sel_hi:[1,0]
	v_mul_f32_e32 v79, 0x45800000, v0
	v_cndmask_b32_e32 v0, v0, v79, vcc
	v_pk_mul_f32 v[36:37], v[36:37], v[0:1] op_sel_hi:[1,0]
	v_pk_mul_f32 v[34:35], v[34:35], v[0:1] op_sel_hi:[1,0]
	v_pk_mul_f32 v[4:5], v[4:5], v[36:37]
	v_pk_mul_f32 v[2:3], v[2:3], v[34:35]
	s_waitcnt vmcnt(9) lgkmcnt(0)
	v_pk_fma_f32 v[4:5], v[8:9], v[4:5], v[24:25]
	v_pk_fma_f32 v[2:3], v[6:7], v[2:3], v[22:23]
	v_lshl_add_u64 v[6:7], v[38:39], 0, v[80:81]
	v_cvt_pk_bf16_f32 v2, v2, v3
	v_cvt_pk_bf16_f32 v3, v4, v5
	global_store_dwordx2 v[86:87], v[2:3], off nt
	v_pk_mul_f32 v[32:33], v[32:33], v[0:1] op_sel_hi:[1,0]
	v_pk_mul_f32 v[30:31], v[30:31], v[0:1] op_sel_hi:[1,0]
	v_pk_mul_f32 v[20:21], v[20:21], v[0:1] op_sel_hi:[1,0]
	v_pk_mul_f32 v[18:19], v[18:19], v[0:1] op_sel_hi:[1,0]
	v_pk_mul_f32 v[12:13], v[12:13], v[0:1] op_sel_hi:[1,0]
	v_pk_mul_f32 v[10:11], v[10:11], v[0:1] op_sel_hi:[1,0]
	s_waitcnt vmcnt(7) lgkmcnt(0)
	v_pk_add_f32 v[8:9], v[174:175], 1.0 op_sel_hi:[1, 0]
	v_pk_mul_f32 v[2:3], v[168:169], v[30:31]
	v_pk_mul_f32 v[4:5], v[170:171], v[32:33]
	v_pk_add_f32 v[6:7], v[172:173], 1.0 op_sel_hi:[1, 0]
	v_pk_fma_f32 v[4:5], v[8:9], v[4:5], v[178:179]
	v_pk_fma_f32 v[2:3], v[6:7], v[2:3], v[176:177]
	v_lshl_add_u64 v[6:7], v[38:39], 0, v[82:83]
	v_cvt_pk_bf16_f32 v2, v2, v3
	v_cvt_pk_bf16_f32 v3, v4, v5
	global_store_dwordx2 v[86:87], v[2:3], off offset:512 nt
	s_waitcnt vmcnt(5) lgkmcnt(0)
	v_pk_add_f32 v[8:9], v[186:187], 1.0 op_sel_hi:[1, 0]
	v_pk_mul_f32 v[2:3], v[180:181], v[18:19]
	v_pk_mul_f32 v[4:5], v[182:183], v[20:21]
	v_pk_add_f32 v[6:7], v[184:185], 1.0 op_sel_hi:[1, 0]
	v_pk_fma_f32 v[4:5], v[8:9], v[4:5], v[190:191]
	v_pk_fma_f32 v[2:3], v[6:7], v[2:3], v[188:189]
	v_lshl_add_u64 v[6:7], v[38:39], 0, v[84:85]
	v_cvt_pk_bf16_f32 v2, v2, v3
	v_cvt_pk_bf16_f32 v3, v4, v5
	global_store_dwordx2 v[86:87], v[2:3], off offset:1024 nt
	s_waitcnt vmcnt(3) lgkmcnt(0)
	v_pk_add_f32 v[8:9], v[198:199], 1.0 op_sel_hi:[1, 0]
	v_pk_mul_f32 v[2:3], v[10:11], v[192:193]
	v_pk_mul_f32 v[4:5], v[12:13], v[194:195]
	v_pk_add_f32 v[6:7], v[196:197], 1.0 op_sel_hi:[1, 0]
	v_pk_fma_f32 v[4:5], v[4:5], v[8:9], v[202:203]
	v_pk_fma_f32 v[2:3], v[2:3], v[6:7], v[200:201]
	s_nop 0
	v_cvt_pk_bf16_f32 v2, v2, v3
	v_cvt_pk_bf16_f32 v3, v4, v5
	global_store_dwordx2 v[86:87], v[2:3], off offset:1536 nt
	s_or_b64 exec, exec, s[34:35]
	v_cmp_gt_i32_e32 vcc, s15, v88
	s_and_saveexec_b64 s[34:35], vcc
	s_cbranch_execnz .LBB0_566

.LBB0_566:
	v_min_i32_e32 v0, 0x8000, v88
	v_ashrrev_i32_e32 v0, 12, v0
	v_lshl_add_u32 v222, v0, 13, v223
	v_mul_i32_i24_e32 v2, 0x1800, v0
	v_ashrrev_i32_e32 v3, 31, v2
	v_lshl_add_u64 v[10:11], v[2:3], 2, s[44:45]
	v_lshl_add_u64 v[18:19], v[10:11], 0, s[8:9]
	v_mov_b32_e32 v79, v1
	v_lshl_add_u64 v[6:7], v[18:19], 0, v[78:79]
	ds_read_b128 v[2:5], v242
	v_lshl_add_u64 v[20:21], v[10:11], 0, v[78:79]
	ds_read_b128 v[6:9], v222 offset:4096
	v_mul_f32_e32 v0, v47, v47
	ds_read_b128 v[10:13], v222
	v_mov_b32_e32 v81, v1
	v_mov_b32_e32 v83, v1
	v_mov_b32_e32 v85, v1
	ds_read_b128 v[168:171], v242 offset:1024
	v_lshl_add_u64 v[172:173], v[18:19], 0, v[80:81]
	ds_read_b128 v[172:175], v222 offset:5120
	ds_read_b128 v[176:179], v222 offset:1024
	ds_read_b128 v[180:183], v242 offset:2048
	v_lshl_add_u64 v[184:185], v[18:19], 0, v[82:83]
	ds_read_b128 v[184:187], v222 offset:6144
	ds_read_b128 v[188:191], v222 offset:2048
	ds_read_b128 v[192:195], v242 offset:3072
	v_lshl_add_u64 v[196:197], v[18:19], 0, v[84:85]
	ds_read_b128 v[196:199], v222 offset:7168
	ds_read_b128 v[200:203], v222 offset:3072
	v_mul_f32_e32 v22, v43, v43
	v_mul_f32_e32 v23, v27, v27
	v_fmac_f32_e32 v0, v46, v46
	v_fmac_f32_e32 v22, v42, v42
	v_mul_f32_e32 v24, v15, v15
	v_fmac_f32_e32 v23, v26, v26
	v_fmac_f32_e32 v0, v48, v48
	v_fmac_f32_e32 v22, v44, v44
	v_fmac_f32_e32 v24, v14, v14
	v_fmac_f32_e32 v23, v28, v28
	v_fmac_f32_e32 v0, v49, v49
	v_fmac_f32_e32 v22, v45, v45
	v_fmac_f32_e32 v24, v16, v16
	v_fmac_f32_e32 v23, v29, v29
	v_add_f32_e32 v0, v22, v0
	v_fmac_f32_e32 v24, v17, v17
	v_add_f32_e32 v0, v23, v0
	v_add_f32_e32 v0, v24, v0
	ds_bpermute_b32 v22, v102, v0
	v_ashrrev_i32_e32 v89, 31, v88
	v_mov_b32_e32 v81, v1
	v_mov_b32_e32 v83, v1
	v_mov_b32_e32 v85, v1
	s_waitcnt lgkmcnt(0)
	v_add_f32_e32 v0, v0, v22
	ds_bpermute_b32 v22, v103, v0
	s_waitcnt lgkmcnt(0)
	v_add_f32_e32 v0, v0, v22
	ds_bpermute_b32 v22, v104, v0
	s_waitcnt lgkmcnt(0)
	v_add_f32_e32 v0, v0, v22
	ds_bpermute_b32 v22, v105, v0
	s_waitcnt lgkmcnt(0)
	v_add_f32_e32 v0, v0, v22
	ds_bpermute_b32 v22, v106, v0
	s_waitcnt lgkmcnt(0)
	v_add_f32_e32 v0, v0, v22
	ds_bpermute_b32 v22, v107, v0
	s_waitcnt lgkmcnt(0)
	v_add_f32_e32 v0, v0, v22
	v_fmamk_f32 v0, v0, 0x3a800000, v218
	v_mul_f32_e32 v22, 0x4b800000, v0
	v_cmp_gt_f32_e32 vcc, s13, v0
	s_waitcnt vmcnt(10) lgkmcnt(0)
	v_pk_add_f32 v[8:9], v[8:9], 1.0 op_sel_hi:[1,0]
	v_cndmask_b32_e32 v0, v0, v22, vcc
	v_rsq_f32_e32 v0, v0
	v_pk_add_f32 v[6:7], v[6:7], 1.0 op_sel_hi:[1,0]
	v_lshlrev_b64 v[22:23], 11, v[88:89]
	v_lshl_add_u64 v[22:23], v[74:75], 0, v[22:23]
	v_mul_f32_e32 v24, 0x45800000, v0
	v_cndmask_b32_e32 v0, v0, v24, vcc
	v_pk_mul_f32 v[24:25], v[48:49], v[0:1] op_sel_hi:[1,0]
	v_pk_mul_f32 v[30:31], v[46:47], v[0:1] op_sel_hi:[1,0]
	v_pk_mul_f32 v[4:5], v[4:5], v[24:25]
	v_pk_mul_f32 v[2:3], v[2:3], v[30:31]
	s_waitcnt vmcnt(9) lgkmcnt(0)
	v_pk_fma_f32 v[4:5], v[8:9], v[4:5], v[12:13]
	v_pk_fma_f32 v[2:3], v[6:7], v[2:3], v[10:11]
	v_lshl_add_u64 v[6:7], v[18:19], 0, v[80:81]
	v_cvt_pk_bf16_f32 v2, v2, v3
	v_cvt_pk_bf16_f32 v3, v4, v5
	global_store_dwordx2 v[22:23], v[2:3], off nt
	v_pk_mul_f32 v[24:25], v[44:45], v[0:1] op_sel_hi:[1,0]
	v_pk_mul_f32 v[30:31], v[42:43], v[0:1] op_sel_hi:[1,0]
	v_pk_mul_f32 v[26:27], v[26:27], v[0:1] op_sel_hi:[1,0]
	v_pk_mul_f32 v[16:17], v[16:17], v[0:1] op_sel_hi:[1,0]
	v_pk_mul_f32 v[14:15], v[14:15], v[0:1] op_sel_hi:[1,0]
	s_waitcnt vmcnt(7) lgkmcnt(0)
	v_pk_add_f32 v[8:9], v[174:175], 1.0 op_sel_hi:[1, 0]
	v_pk_mul_f32 v[2:3], v[168:169], v[30:31]
	v_pk_mul_f32 v[4:5], v[170:171], v[24:25]
	v_pk_add_f32 v[6:7], v[172:173], 1.0 op_sel_hi:[1, 0]
	v_pk_fma_f32 v[4:5], v[8:9], v[4:5], v[178:179]
	v_pk_fma_f32 v[2:3], v[6:7], v[2:3], v[176:177]
	v_lshl_add_u64 v[6:7], v[18:19], 0, v[82:83]
	v_cvt_pk_bf16_f32 v2, v2, v3
	v_cvt_pk_bf16_f32 v3, v4, v5
	global_store_dwordx2 v[22:23], v[2:3], off offset:512 nt
	v_pk_mul_f32 v[24:25], v[28:29], v[0:1] op_sel_hi:[1,0]
	s_waitcnt vmcnt(5) lgkmcnt(0)
	v_pk_add_f32 v[8:9], v[186:187], 1.0 op_sel_hi:[1, 0]
	v_pk_mul_f32 v[2:3], v[180:181], v[26:27]
	v_pk_mul_f32 v[4:5], v[182:183], v[24:25]
	v_pk_add_f32 v[6:7], v[184:185], 1.0 op_sel_hi:[1, 0]
	v_pk_fma_f32 v[4:5], v[8:9], v[4:5], v[190:191]
	v_pk_fma_f32 v[2:3], v[6:7], v[2:3], v[188:189]
	v_lshl_add_u64 v[6:7], v[18:19], 0, v[84:85]
	v_cvt_pk_bf16_f32 v2, v2, v3
	v_cvt_pk_bf16_f32 v3, v4, v5
	global_store_dwordx2 v[22:23], v[2:3], off offset:1024 nt
	s_waitcnt vmcnt(3) lgkmcnt(0)
	v_pk_add_f32 v[8:9], v[198:199], 1.0 op_sel_hi:[1, 0]
	v_pk_mul_f32 v[2:3], v[14:15], v[192:193]
	v_pk_mul_f32 v[4:5], v[16:17], v[194:195]
	v_pk_add_f32 v[6:7], v[196:197], 1.0 op_sel_hi:[1, 0]
	v_pk_fma_f32 v[4:5], v[4:5], v[8:9], v[202:203]
	v_pk_fma_f32 v[2:3], v[2:3], v[6:7], v[200:201]
	s_nop 0
	v_cvt_pk_bf16_f32 v2, v2, v3
	v_cvt_pk_bf16_f32 v3, v4, v5
	global_store_dwordx2 v[22:23], v[2:3], off offset:1536 nt
	s_or_b64 exec, exec, s[34:35]
	v_cmp_gt_i32_e32 vcc, s15, v90
	s_and_saveexec_b64 s[34:35], vcc
	s_cbranch_execz .LBB0_529
.LBB0_567:
	v_min_i32_e32 v0, 0x8000, v90
	v_ashrrev_i32_e32 v0, 12, v0
	v_lshl_add_u32 v222, v0, 13, v223
	v_mul_i32_i24_e32 v2, 0x1800, v0
	v_ashrrev_i32_e32 v3, 31, v2
	v_lshl_add_u64 v[10:11], v[2:3], 2, s[44:45]
	v_lshl_add_u64 v[14:15], v[10:11], 0, s[8:9]
	v_mov_b32_e32 v79, v1
	v_lshl_add_u64 v[6:7], v[14:15], 0, v[78:79]
	ds_read_b128 v[2:5], v242
	v_lshl_add_u64 v[16:17], v[10:11], 0, v[78:79]
	ds_read_b128 v[6:9], v222 offset:4096
	v_mul_f32_e32 v0, v63, v63
	ds_read_b128 v[10:13], v222
	v_mov_b32_e32 v81, v1
	v_mov_b32_e32 v83, v1
	v_mov_b32_e32 v85, v1
	ds_read_b128 v[168:171], v242 offset:1024
	v_lshl_add_u64 v[172:173], v[14:15], 0, v[80:81]
	ds_read_b128 v[172:175], v222 offset:5120
	ds_read_b128 v[176:179], v222 offset:1024
	ds_read_b128 v[180:183], v242 offset:2048
	v_lshl_add_u64 v[184:185], v[14:15], 0, v[82:83]
	ds_read_b128 v[184:187], v222 offset:6144
	ds_read_b128 v[188:191], v222 offset:2048
	ds_read_b128 v[192:195], v242 offset:3072
	v_lshl_add_u64 v[196:197], v[14:15], 0, v[84:85]
	ds_read_b128 v[196:199], v222 offset:7168
	ds_read_b128 v[200:203], v222 offset:3072
	v_mul_f32_e32 v18, v59, v59
	v_mul_f32_e32 v19, v55, v55
	v_fmac_f32_e32 v0, v62, v62
	v_fmac_f32_e32 v18, v58, v58
	v_mul_f32_e32 v20, v51, v51
	v_fmac_f32_e32 v19, v54, v54
	v_fmac_f32_e32 v0, v64, v64
	v_fmac_f32_e32 v18, v60, v60
	v_fmac_f32_e32 v20, v50, v50
	v_fmac_f32_e32 v19, v56, v56
	v_fmac_f32_e32 v0, v65, v65
	v_fmac_f32_e32 v18, v61, v61
	v_fmac_f32_e32 v20, v52, v52
	v_fmac_f32_e32 v19, v57, v57
	v_add_f32_e32 v0, v18, v0
	v_fmac_f32_e32 v20, v53, v53
	v_add_f32_e32 v0, v19, v0
	v_add_f32_e32 v0, v20, v0
	ds_bpermute_b32 v18, v102, v0
	v_ashrrev_i32_e32 v91, 31, v90
	v_mov_b32_e32 v81, v1
	v_mov_b32_e32 v83, v1
	v_mov_b32_e32 v85, v1
	s_waitcnt lgkmcnt(0)
	v_add_f32_e32 v0, v0, v18
	ds_bpermute_b32 v18, v103, v0
	s_waitcnt lgkmcnt(0)
	v_add_f32_e32 v0, v0, v18
	ds_bpermute_b32 v18, v104, v0
	s_waitcnt lgkmcnt(0)
	v_add_f32_e32 v0, v0, v18
	ds_bpermute_b32 v18, v105, v0
	s_waitcnt lgkmcnt(0)
	v_add_f32_e32 v0, v0, v18
	ds_bpermute_b32 v18, v106, v0
	s_waitcnt lgkmcnt(0)
	v_add_f32_e32 v0, v0, v18
	ds_bpermute_b32 v18, v107, v0
	s_waitcnt lgkmcnt(0)
	v_add_f32_e32 v0, v0, v18
	v_fmamk_f32 v0, v0, 0x3a800000, v218
	v_mul_f32_e32 v18, 0x4b800000, v0
	v_cmp_gt_f32_e32 vcc, s13, v0
	s_waitcnt vmcnt(10) lgkmcnt(0)
	v_pk_add_f32 v[8:9], v[8:9], 1.0 op_sel_hi:[1,0]
	v_cndmask_b32_e32 v0, v0, v18, vcc
	v_rsq_f32_e32 v0, v0
	v_pk_add_f32 v[6:7], v[6:7], 1.0 op_sel_hi:[1,0]
	v_lshlrev_b64 v[18:19], 11, v[90:91]
	v_lshl_add_u64 v[18:19], v[74:75], 0, v[18:19]
	v_mul_f32_e32 v20, 0x45800000, v0
	v_cndmask_b32_e32 v0, v0, v20, vcc
	v_pk_mul_f32 v[20:21], v[64:65], v[0:1] op_sel_hi:[1,0]
	v_pk_mul_f32 v[22:23], v[62:63], v[0:1] op_sel_hi:[1,0]
	v_pk_mul_f32 v[4:5], v[4:5], v[20:21]
	v_pk_mul_f32 v[2:3], v[2:3], v[22:23]
	s_waitcnt vmcnt(9) lgkmcnt(0)
	v_pk_fma_f32 v[4:5], v[8:9], v[4:5], v[12:13]
	v_pk_fma_f32 v[2:3], v[6:7], v[2:3], v[10:11]
	v_lshl_add_u64 v[6:7], v[14:15], 0, v[80:81]
	v_cvt_pk_bf16_f32 v2, v2, v3
	v_cvt_pk_bf16_f32 v3, v4, v5
	global_store_dwordx2 v[18:19], v[2:3], off nt
	v_pk_mul_f32 v[20:21], v[60:61], v[0:1] op_sel_hi:[1,0]
	v_pk_mul_f32 v[22:23], v[58:59], v[0:1] op_sel_hi:[1,0]
	s_waitcnt vmcnt(7) lgkmcnt(0)
	v_pk_add_f32 v[8:9], v[174:175], 1.0 op_sel_hi:[1, 0]
	v_pk_mul_f32 v[2:3], v[168:169], v[22:23]
	v_pk_mul_f32 v[4:5], v[170:171], v[20:21]
	v_pk_add_f32 v[6:7], v[172:173], 1.0 op_sel_hi:[1, 0]
	v_pk_fma_f32 v[4:5], v[8:9], v[4:5], v[178:179]
	v_pk_fma_f32 v[2:3], v[6:7], v[2:3], v[176:177]
	v_lshl_add_u64 v[6:7], v[14:15], 0, v[82:83]
	v_cvt_pk_bf16_f32 v2, v2, v3
	v_cvt_pk_bf16_f32 v3, v4, v5
	global_store_dwordx2 v[18:19], v[2:3], off offset:512 nt
	v_pk_mul_f32 v[20:21], v[56:57], v[0:1] op_sel_hi:[1,0]
	v_pk_mul_f32 v[22:23], v[54:55], v[0:1] op_sel_hi:[1,0]
	s_waitcnt vmcnt(5) lgkmcnt(0)
	v_pk_add_f32 v[8:9], v[186:187], 1.0 op_sel_hi:[1, 0]
	v_pk_mul_f32 v[2:3], v[180:181], v[22:23]
	v_pk_mul_f32 v[4:5], v[182:183], v[20:21]
	v_pk_add_f32 v[6:7], v[184:185], 1.0 op_sel_hi:[1, 0]
	v_pk_fma_f32 v[4:5], v[8:9], v[4:5], v[190:191]
	v_pk_fma_f32 v[2:3], v[6:7], v[2:3], v[188:189]
	v_lshl_add_u64 v[6:7], v[14:15], 0, v[84:85]
	v_cvt_pk_bf16_f32 v2, v2, v3
	v_cvt_pk_bf16_f32 v3, v4, v5
	global_store_dwordx2 v[18:19], v[2:3], off offset:1024 nt
	v_pk_mul_f32 v[14:15], v[52:53], v[0:1] op_sel_hi:[1,0]
	v_pk_mul_f32 v[16:17], v[50:51], v[0:1] op_sel_hi:[1,0]
	s_waitcnt vmcnt(3) lgkmcnt(0)
	v_pk_add_f32 v[8:9], v[198:199], 1.0 op_sel_hi:[1, 0]
	v_pk_mul_f32 v[2:3], v[16:17], v[192:193]
	v_pk_mul_f32 v[4:5], v[14:15], v[194:195]
	v_pk_add_f32 v[6:7], v[196:197], 1.0 op_sel_hi:[1, 0]
	v_pk_fma_f32 v[4:5], v[4:5], v[8:9], v[202:203]
	v_pk_fma_f32 v[2:3], v[2:3], v[6:7], v[200:201]
	s_nop 0
	v_cvt_pk_bf16_f32 v2, v2, v3
	v_cvt_pk_bf16_f32 v3, v4, v5
	global_store_dwordx2 v[18:19], v[2:3], off offset:1536 nt
	s_branch .LBB0_529
	s_nop 0
	s_nop 0
